# grid barrier: every workgroup writes back L2 (buffer_wbl2) before it arrives, XCD leader no longer does
# baseline (speedup 1.0000x reference)
.LBB0_196:
	v_readlane_b32 s4, v251, 19
	v_readlane_b32 s5, v251, 20
	v_cvt_f32_u32_e32 v1, v2
	v_sub_u32_e32 v4, 0, v2
	v_rcp_iflag_f32_e32 v1, v1
	s_nop 1
	buffer_wbl2 sc1
	s_waitcnt vmcnt(0)
	global_atomic_add v3, v97, v197, s[4:5] sc0
	v_mul_f32_e32 v1, 0x4f7ffffe, v1
	v_cvt_u32_f32_e32 v1, v1
	v_mul_lo_u32 v4, v4, v1
	v_mul_hi_u32 v4, v1, v4
	v_add_u32_e32 v1, v1, v4
	s_waitcnt vmcnt(0)
	v_mul_hi_u32 v1, v3, v1
	v_mul_lo_u32 v4, v1, v2
	v_sub_u32_e32 v4, v3, v4
	v_add_u32_e32 v5, 1, v1
	v_cmp_ge_u32_e32 vcc, v4, v2
	v_add_u32_e32 v3, 1, v3
	s_nop 0
	v_cndmask_b32_e32 v1, v1, v5, vcc
	v_sub_u32_e32 v5, v4, v2
	v_cndmask_b32_e32 v4, v4, v5, vcc
	v_add_u32_e32 v5, 1, v1
	v_cmp_ge_u32_e32 vcc, v4, v2
	s_nop 1
	v_cndmask_b32_e32 v1, v1, v5, vcc
	v_mul_lo_u32 v4, v2, v1
	v_add_u32_e32 v2, v4, v2
	v_cmp_ne_u32_e32 vcc, v3, v2
	s_and_saveexec_b64 s[4:5], vcc
	s_xor_b64 s[8:9], exec, s[4:5]
	s_cbranch_execz .LBB0_210
	v_readlane_b32 s4, v251, 21
	v_readlane_b32 s5, v251, 22
	s_waitcnt lgkmcnt(0)
	s_nop 3
	global_load_dword v0, v97, s[4:5] sc1
	s_waitcnt vmcnt(0)
	v_cmp_eq_u32_e32 vcc, v0, v1
	s_and_saveexec_b64 s[10:11], vcc
	s_cbranch_execz .LBB0_209
	s_mov_b32 s3, 1
	s_mov_b64 s[12:13], 0
	s_branch .LBB0_200

.LBB0_210:
	s_andn2_saveexec_b64 s[4:5], s[8:9]
	s_cbranch_execz .LBB0_228
	s_mov_b64 s[8:9], exec
	s_nop 0
	s_waitcnt lgkmcnt(0)
	s_waitcnt vmcnt(0)
	v_mbcnt_lo_u32_b32 v1, s8, 0
	v_mbcnt_hi_u32_b32 v1, s9, v1
	v_cmp_eq_u32_e32 vcc, 0, v1
	s_and_saveexec_b64 s[10:11], vcc
	s_cbranch_execz .LBB0_213
	s_bcnt1_i32_b64 s3, s[8:9]
	v_readlane_b32 s4, v251, 23
	v_mov_b32_e32 v2, s3
	v_readlane_b32 s5, v251, 24
	s_nop 4
	global_atomic_add v2, v97, v2, s[4:5] sc0

.LBB0_742:
	v_readlane_b32 s2, v251, 19
	v_readlane_b32 s3, v251, 20
	v_cvt_f32_u32_e32 v1, v2
	v_sub_u32_e32 v4, 0, v2
	v_rcp_iflag_f32_e32 v1, v1
	s_nop 1
	buffer_wbl2 sc1
	s_waitcnt vmcnt(0)
	global_atomic_add v3, v97, v197, s[2:3] sc0
	v_mul_f32_e32 v1, 0x4f7ffffe, v1
	v_cvt_u32_f32_e32 v1, v1
	v_mul_lo_u32 v4, v4, v1
	v_mul_hi_u32 v4, v1, v4
	v_add_u32_e32 v1, v1, v4
	s_waitcnt vmcnt(0)
	v_mul_hi_u32 v1, v3, v1
	v_mul_lo_u32 v4, v1, v2
	v_sub_u32_e32 v4, v3, v4
	v_add_u32_e32 v5, 1, v1
	v_cmp_ge_u32_e32 vcc, v4, v2
	v_add_u32_e32 v3, 1, v3
	s_nop 0
	v_cndmask_b32_e32 v1, v1, v5, vcc
	v_sub_u32_e32 v5, v4, v2
	v_cndmask_b32_e32 v4, v4, v5, vcc
	v_add_u32_e32 v5, 1, v1
	v_cmp_ge_u32_e32 vcc, v4, v2
	s_nop 1
	v_cndmask_b32_e32 v1, v1, v5, vcc
	v_mul_lo_u32 v4, v2, v1
	v_add_u32_e32 v2, v4, v2
	v_cmp_ne_u32_e32 vcc, v3, v2
	s_and_saveexec_b64 s[2:3], vcc
	s_xor_b64 s[8:9], exec, s[2:3]
	s_cbranch_execz .LBB0_756
	v_readlane_b32 s2, v251, 21
	v_readlane_b32 s3, v251, 22
	s_waitcnt lgkmcnt(0)
	s_nop 3
	global_load_dword v0, v97, s[2:3] sc1
	s_waitcnt vmcnt(0)
	v_cmp_eq_u32_e32 vcc, v0, v1
	s_and_saveexec_b64 s[10:11], vcc
	s_cbranch_execz .LBB0_755
	s_mov_b32 s2, 1
	s_mov_b64 s[12:13], 0
	s_branch .LBB0_746

.LBB0_756:
	s_andn2_saveexec_b64 s[2:3], s[8:9]
	s_cbranch_execz .LBB0_774
	s_mov_b64 s[8:9], exec
	s_nop 0
	s_waitcnt lgkmcnt(0)
	s_waitcnt vmcnt(0)
	v_mbcnt_lo_u32_b32 v1, s8, 0
	v_mbcnt_hi_u32_b32 v1, s9, v1
	v_cmp_eq_u32_e32 vcc, 0, v1
	s_and_saveexec_b64 s[10:11], vcc
	s_cbranch_execz .LBB0_759
	s_bcnt1_i32_b64 s2, s[8:9]
	v_mov_b32_e32 v2, s2
	v_readlane_b32 s2, v251, 23
	v_readlane_b32 s3, v251, 24
	s_nop 4
	global_atomic_add v2, v97, v2, s[2:3] sc0

.LBB0_1453:
	s_mov_b64 s[8:9], exec
	s_nop 0
	s_waitcnt lgkmcnt(0)
	s_waitcnt vmcnt(0)
	v_mbcnt_lo_u32_b32 v1, s8, 0
	v_mbcnt_hi_u32_b32 v1, s9, v1
	v_cmp_eq_u32_e32 vcc, 0, v1
	s_and_saveexec_b64 s[10:11], vcc
	s_cbranch_execz .LBB0_1455
	s_bcnt1_i32_b64 s2, s[8:9]
	v_mov_b32_e32 v2, s2
	v_readlane_b32 s2, v251, 23
	v_readlane_b32 s3, v251, 24
	s_nop 4
	global_atomic_add v2, v97, v2, s[2:3] sc0
